# norm phases 9/12/15: residual-stream row loads (4 HI/LO pairs + 4 delta loads) issued together with counted vmcnt instead of one serialized round trip each
# speedup vs baseline: 1.0094x; 1.0094x over previous
; #define GAS __attribute__((address_space(1)))
; __device__ __forceinline__ void h24_load(const unsigned char* Hb, size_t r, int lane, float (&v)[4][8]) {
; #pragma unroll
;     for (int j = 0; j < 4; ++j) { const size_t e = r * 2048 + 8 * (lane + 64 * j);
;         const v4u hi = __builtin_nontemporal_load((const GAS v4u*)(Hb + e * 2)); const unsigned lo = __builtin_nontemporal_load((const GAS unsigned*)(Hb + H_LO_OFF + (e >> 1)));
; #pragma unroll
;         for (int q = 0; q < 4; ++q) {
;             v[j][2 * q] = __builtin_bit_cast(float, ((hi[q] & 0xffffu) << 16) | (((lo >> (8 * q)) & 0xfu) << 12));
;             v[j][2 * q + 1] = __builtin_bit_cast(float, (hi[q] & 0xffff0000u) | (((lo >> (8 * q + 4)) & 0xfu) << 12)); } }
; }
; __device__ __forceinline__ void norm_phase(bool from_input, int gw, int NGW, int lane_in, float* H, const float* x_in, const float* c_in, const float* gain, const float* modL, int js, int jc, bf16* XN, ...
;     ...
;         if (from_input || (pend && s_from_input)) f32_load8_nt(s < 256 ? c_in + ((size_t)b * 256 + s) * 2048 : x_in + ((size_t)b * 8192 + (s - 256)) * 2048, lane, v);
;         else h24_load(Hb, (size_t)r, lane, v);
;         if (DLT && s >= 256) { bf16_add8(DLT + (size_t)r * 2048, lane, v); h24_store(Hb, (size_t)r, lane, v); }
.LBB0_1136:
	s_lshl_b64 s[38:39], s[20:21], 11
	v_mov_b32_e32 v37, s39
	v_or_b32_e32 v36, s38, v40
	v_lshl_add_u64 v[124:125], v[36:37], 1, s[90:91]
	v_lshrrev_b64 v[36:37], 1, v[36:37]
	v_lshl_add_u64 v[126:127], s[78:79], 0, v[36:37]
	global_load_dwordx4 v[208:211], v[124:125], off nt
	global_load_dword v242, v[126:127], off nt
	v_mov_b32_e32 v207, s39
	v_or_b32_e32 v206, s38, v42
	v_lshl_add_u64 v[136:137], v[206:207], 1, s[90:91]
	v_lshrrev_b64 v[206:207], 1, v[206:207]
	v_lshl_add_u64 v[138:139], s[78:79], 0, v[206:207]
	global_load_dwordx4 v[212:215], v[136:137], off nt
	global_load_dword v243, v[138:139], off nt
	v_mov_b32_e32 v207, s39
	v_or_b32_e32 v206, s38, v44
	v_lshl_add_u64 v[140:141], v[206:207], 1, s[90:91]
	v_lshrrev_b64 v[206:207], 1, v[206:207]
	v_lshl_add_u64 v[142:143], s[78:79], 0, v[206:207]
	global_load_dwordx4 v[216:219], v[140:141], off nt
	global_load_dword v244, v[142:143], off nt
	v_mov_b32_e32 v207, s39
	v_or_b32_e32 v206, s38, v46
	v_lshl_add_u64 v[144:145], v[206:207], 1, s[90:91]
	v_lshrrev_b64 v[206:207], 1, v[206:207]
	v_lshl_add_u64 v[146:147], s[78:79], 0, v[206:207]
	global_load_dwordx4 v[220:223], v[144:145], off nt
	global_load_dword v245, v[146:147], off nt
	v_lshl_add_u64 v[240:241], v[48:49], 0, s[38:39]
	v_lshl_add_u64 v[240:241], v[240:241], 0, s[38:39]
	global_load_dwordx4 v[224:227], v[240:241], off nt
	global_load_dwordx4 v[228:231], v[240:241], off offset:1024 nt
	global_load_dwordx4 v[232:235], v[240:241], off offset:2048 nt
	global_load_dwordx4 v[236:239], v[240:241], off offset:3072 nt
	s_cmpk_lt_u32 s11, 0x100
	s_waitcnt vmcnt(11)
	v_and_b32_e32 v37, 0xffff0000, v208
	s_waitcnt vmcnt(10)
	v_lshlrev_b32_e32 v39, 12, v242
	v_lshlrev_b32_e32 v32, 16, v208
	v_lshlrev_b32_e32 v38, 8, v242
	v_and_b32_e32 v39, 0xf000, v39
	v_and_b32_e32 v38, 0xf000, v38
	v_or_b32_e32 v108, v39, v32
	v_lshlrev_b32_e32 v32, 4, v242
	v_or_b32_e32 v109, v38, v37
	v_and_b32_e32 v37, 0xffff0000, v209
	v_lshlrev_b32_e32 v33, 16, v209
	v_and_b32_e32 v38, 0xf000, v242
	v_and_b32_e32 v32, 0xf000, v32
	v_or_b32_e32 v111, v38, v37
	v_or_b32_e32 v110, v32, v33
	v_and_b32_e32 v32, 0xffff0000, v210
	v_lshlrev_b32_e32 v33, 16, v210
	v_lshrrev_b32_e32 v34, 8, v242
	v_lshrrev_b32_e32 v37, 4, v242
	v_and_b32_e32 v34, 0xf000, v34
	v_and_b32_e32 v37, 0xf000, v37
	v_or_b32_e32 v113, v34, v32
	v_or_b32_e32 v112, v37, v33
	v_and_b32_e32 v32, 0xffff0000, v211
	v_lshlrev_b32_e32 v33, 16, v211
	v_lshrrev_b32_e32 v34, 12, v242
	v_and_b32_sdwa v35, v242, s5 dst_sel:DWORD dst_unused:UNUSED_PAD src0_sel:WORD_1 src1_sel:DWORD
	v_mov_b32_e32 v37, s39
	v_or_b32_e32 v36, s38, v42
	v_lshl_add_u64 v[136:137], v[36:37], 1, s[90:91]
	v_lshrrev_b64 v[36:37], 1, v[36:37]
	v_and_b32_e32 v34, 0xf000, v34
	v_lshl_add_u64 v[138:139], s[78:79], 0, v[36:37]
	v_or_b32_e32 v115, v35, v32
	v_or_b32_e32 v114, v34, v33
	s_waitcnt vmcnt(9)
	v_and_b32_e32 v37, 0xffff0000, v212
	s_waitcnt vmcnt(8)
	v_lshlrev_b32_e32 v39, 12, v243
	v_lshlrev_b32_e32 v32, 16, v212
	v_lshlrev_b32_e32 v38, 8, v243
	v_and_b32_e32 v39, 0xf000, v39
	v_and_b32_e32 v38, 0xf000, v38
	v_or_b32_e32 v116, v39, v32
	v_lshlrev_b32_e32 v32, 4, v243
	v_or_b32_e32 v117, v38, v37
	v_and_b32_e32 v37, 0xffff0000, v213
	v_lshlrev_b32_e32 v33, 16, v213
	v_and_b32_e32 v38, 0xf000, v243
	v_and_b32_e32 v32, 0xf000, v32
	v_or_b32_e32 v119, v38, v37
	v_or_b32_e32 v118, v32, v33
	v_and_b32_e32 v32, 0xffff0000, v214
	v_lshlrev_b32_e32 v33, 16, v214
	v_lshrrev_b32_e32 v34, 8, v243
	v_lshrrev_b32_e32 v37, 4, v243
	v_and_b32_e32 v34, 0xf000, v34
	v_and_b32_e32 v37, 0xf000, v37
	v_or_b32_e32 v121, v34, v32
	v_or_b32_e32 v120, v37, v33
	v_and_b32_e32 v32, 0xffff0000, v215
	v_lshlrev_b32_e32 v33, 16, v215
	v_lshrrev_b32_e32 v34, 12, v243
	v_and_b32_sdwa v35, v243, s5 dst_sel:DWORD dst_unused:UNUSED_PAD src0_sel:WORD_1 src1_sel:DWORD
	v_mov_b32_e32 v37, s39
	v_or_b32_e32 v36, s38, v44
	v_lshl_add_u64 v[140:141], v[36:37], 1, s[90:91]
	v_lshrrev_b64 v[36:37], 1, v[36:37]
	v_and_b32_e32 v34, 0xf000, v34
	v_lshl_add_u64 v[142:143], s[78:79], 0, v[36:37]
	v_or_b32_e32 v123, v35, v32
	v_or_b32_e32 v122, v34, v33
	s_waitcnt vmcnt(7)
	v_and_b32_e32 v37, 0xffff0000, v216
	s_waitcnt vmcnt(6)
	v_lshlrev_b32_e32 v39, 12, v244
	v_lshlrev_b32_e32 v32, 16, v216
	v_lshlrev_b32_e32 v38, 8, v244
	v_and_b32_e32 v39, 0xf000, v39
	v_and_b32_e32 v38, 0xf000, v38
	v_or_b32_e32 v128, v39, v32
	v_lshlrev_b32_e32 v32, 4, v244
	v_or_b32_e32 v129, v38, v37
	v_and_b32_e32 v37, 0xffff0000, v217
	v_lshlrev_b32_e32 v33, 16, v217
	v_and_b32_e32 v38, 0xf000, v244
	v_and_b32_e32 v32, 0xf000, v32
	v_or_b32_e32 v131, v38, v37
	v_or_b32_e32 v130, v32, v33
	v_and_b32_e32 v32, 0xffff0000, v218
	v_lshlrev_b32_e32 v33, 16, v218
	v_lshrrev_b32_e32 v34, 8, v244
	v_lshrrev_b32_e32 v37, 4, v244
	v_and_b32_e32 v34, 0xf000, v34
	v_and_b32_e32 v37, 0xf000, v37
	v_or_b32_e32 v133, v34, v32
	v_or_b32_e32 v132, v37, v33
	v_and_b32_e32 v32, 0xffff0000, v219
	v_lshlrev_b32_e32 v33, 16, v219
	v_lshrrev_b32_e32 v34, 12, v244
	v_and_b32_sdwa v35, v244, s5 dst_sel:DWORD dst_unused:UNUSED_PAD src0_sel:WORD_1 src1_sel:DWORD
	v_mov_b32_e32 v37, s39
	v_or_b32_e32 v36, s38, v46
	v_lshl_add_u64 v[144:145], v[36:37], 1, s[90:91]
	v_lshrrev_b64 v[36:37], 1, v[36:37]
	v_and_b32_e32 v34, 0xf000, v34
	v_lshl_add_u64 v[146:147], s[78:79], 0, v[36:37]
	v_or_b32_e32 v135, v35, v32
	v_or_b32_e32 v134, v34, v33
	s_waitcnt vmcnt(5)
	v_and_b32_e32 v37, 0xffff0000, v220
	s_waitcnt vmcnt(4)
	v_lshlrev_b32_e32 v39, 12, v245
	v_lshlrev_b32_e32 v32, 16, v220
	v_lshlrev_b32_e32 v38, 8, v245
	v_and_b32_e32 v39, 0xf000, v39
	v_and_b32_e32 v38, 0xf000, v38
	v_or_b32_e32 v148, v39, v32
	v_lshlrev_b32_e32 v32, 4, v245
	v_or_b32_e32 v149, v38, v37
	v_and_b32_e32 v37, 0xffff0000, v221
	v_lshlrev_b32_e32 v33, 16, v221
	v_and_b32_e32 v32, 0xf000, v32
	v_and_b32_e32 v38, 0xf000, v245
	v_or_b32_e32 v150, v32, v33
	v_and_b32_e32 v32, 0xffff0000, v222
	v_lshlrev_b32_e32 v33, 16, v222
	v_lshrrev_b32_e32 v34, 8, v245
	v_or_b32_e32 v151, v38, v37
	v_lshrrev_b32_e32 v37, 4, v245
	v_and_b32_e32 v34, 0xf000, v34
	v_and_b32_e32 v37, 0xf000, v37
	v_or_b32_e32 v153, v34, v32
	v_lshrrev_b32_e32 v34, 12, v245
	v_or_b32_e32 v152, v37, v33
	v_and_b32_e32 v32, 0xffff0000, v223
	v_lshlrev_b32_e32 v33, 16, v223
	v_and_b32_sdwa v35, v245, s5 dst_sel:DWORD dst_unused:UNUSED_PAD src0_sel:WORD_1 src1_sel:DWORD
	v_and_b32_e32 v34, 0xf000, v34
	v_or_b32_e32 v155, v35, v32
	v_or_b32_e32 v154, v34, v33
	s_cbranch_scc1 .LBB0_1138
; #define GAS __attribute__((address_space(1)))
; __device__ __forceinline__ void h24_store(unsigned char* Hb, size_t r, int lane, const float (&v)[4][8]) {
; #pragma unroll
;     for (int j = 0; j < 4; ++j) { const size_t e = r * 2048 + 8 * (lane + 64 * j); unsigned u[8];
; #pragma unroll
;         for (int q = 0; q < 8; ++q) u[q] = __builtin_bit_cast(unsigned, v[j][q]) + 0x800u;
;         v4u hi; unsigned lo = 0u;
; #pragma unroll
;         for (int q = 0; q < 4; ++q) hi[q] = (u[2 * q] >> 16) | (u[2 * q + 1] & 0xffff0000u);
; #pragma unroll
;         for (int q = 0; q < 8; ++q) lo |= ((u[q] >> 12) & 0xfu) << (4 * q);
;         __builtin_nontemporal_store(hi, (GAS v4u*)(Hb + e * 2)); __builtin_nontemporal_store(lo, (GAS unsigned*)(Hb + H_LO_OFF + (e >> 1))); }
; }
; __device__ __forceinline__ void f32_load8(const float* row, int lane, float (&v)[4][8]) {
; #pragma unroll
;     for (int j = 0; j < 4; ++j) { const GAS f32x4* p = (const GAS f32x4*)(row + 8 * (lane + 64 * j)); const f32x4 a = p[0], b = p[1];
; #pragma unroll
;         for (int q = 0; q < 4; ++q) { v[j][q] = a[q]; v[j][4 + q] = b[q]; } }
; }
; __device__ __forceinline__ void f32_load8_nt(const float* row, int lane, float (&v)[4][8]) {
; #pragma unroll
;     for (int j = 0; j < 4; ++j) { const GAS f32x4* p = (const GAS f32x4*)(row + 8 * (lane + 64 * j)); const f32x4 a = __builtin_nontemporal_load(p), b = __builtin_nontemporal_load(p + 1);
; #pragma unroll
;         for (int q = 0; q < 4; ++q) { v[j][q] = a[q]; v[j][4 + q] = b[q]; } }
; }
; __device__ __forceinline__ void bf16_add8(const bf16* row, int lane, float (&v)[4][8]) {
; #pragma unroll
;     for (int j = 0; j < 4; ++j) { const v4u d = __builtin_nontemporal_load((const GAS v4u*)(row + 8 * (lane + 64 * j)));
; #pragma unroll
;         for (int q = 0; q < 4; ++q) { v[j][2 * q] += bf2f(d[q] & 0xffffu); v[j][2 * q + 1] += bf2f(d[q] >> 16); } }
; }
	s_lshl_b64 s[38:39], s[20:21], 12
	v_lshl_add_u64 v[36:37], v[48:49], 0, s[38:39]
	s_waitcnt vmcnt(3)
	v_and_b32_e32 v39, 0xffff0000, v224
	v_lshlrev_b32_e32 v38, 16, v224
	v_pk_add_f32 v[108:109], v[108:109], v[38:39]
	v_and_b32_e32 v39, 0xffff0000, v225
	v_lshlrev_b32_e32 v38, 16, v225
	v_and_b32_e32 v33, 0xffff0000, v226
	v_lshlrev_b32_e32 v32, 16, v226
	v_pk_add_f32 v[112:113], v[112:113], v[32:33]
	v_and_b32_e32 v33, 0xffff0000, v227
	v_lshlrev_b32_e32 v32, 16, v227
	v_pk_add_f32 v[114:115], v[114:115], v[32:33]
	v_pk_add_f32 v[110:111], v[110:111], v[38:39]
	v_add_u32_e32 v45, 0x800, v112
	v_add_u32_e32 v47, 0x800, v114
	v_add_u32_e32 v157, 0x800, v113
	v_add_u32_e32 v156, 0x800, v115
	s_waitcnt vmcnt(2)
	v_and_b32_e32 v39, 0xffff0000, v228
	v_lshlrev_b32_e32 v38, 16, v228
	v_pk_add_f32 v[116:117], v[116:117], v[38:39]
	v_and_b32_e32 v39, 0xffff0000, v229
	v_lshlrev_b32_e32 v38, 16, v229
	v_and_b32_e32 v33, 0xffff0000, v230
	v_lshlrev_b32_e32 v32, 16, v230
	v_pk_add_f32 v[120:121], v[120:121], v[32:33]
	v_and_b32_e32 v33, 0xffff0000, v231
	v_lshlrev_b32_e32 v32, 16, v231
	v_pk_add_f32 v[122:123], v[122:123], v[32:33]
	v_pk_add_f32 v[118:119], v[118:119], v[38:39]
	s_waitcnt vmcnt(1)
	v_and_b32_e32 v39, 0xffff0000, v232
	v_lshlrev_b32_e32 v38, 16, v232
	v_pk_add_f32 v[128:129], v[128:129], v[38:39]
	v_and_b32_e32 v39, 0xffff0000, v233
	v_lshlrev_b32_e32 v38, 16, v233
	v_and_b32_e32 v33, 0xffff0000, v234
	v_lshlrev_b32_e32 v32, 16, v234
	v_pk_add_f32 v[132:133], v[132:133], v[32:33]
	v_and_b32_e32 v33, 0xffff0000, v235
	v_lshlrev_b32_e32 v32, 16, v235
	v_pk_add_f32 v[134:135], v[134:135], v[32:33]
	v_pk_add_f32 v[130:131], v[130:131], v[38:39]
	v_add_u32_e32 v38, 0x800, v111
	v_add_u32_e32 v39, 0x800, v109
	s_waitcnt vmcnt(0)
	v_and_b32_e32 v37, 0xffff0000, v236
	v_lshlrev_b32_e32 v36, 16, v236
	v_pk_add_f32 v[148:149], v[148:149], v[36:37]
	v_and_b32_e32 v37, 0xffff0000, v237
	v_lshlrev_b32_e32 v36, 16, v237
	v_and_b32_e32 v33, 0xffff0000, v238
	v_lshlrev_b32_e32 v32, 16, v238
	v_pk_add_f32 v[150:151], v[150:151], v[36:37]
	v_pk_add_f32 v[152:153], v[152:153], v[32:33]
	v_and_b32_e32 v33, 0xffff0000, v239
	v_lshlrev_b32_e32 v32, 16, v239
	v_add_u32_e32 v36, 0x800, v108
	v_add_u32_e32 v37, 0x800, v110
	v_pk_add_f32 v[154:155], v[154:155], v[32:33]
	v_lshrrev_b32_e32 v33, 16, v37
	v_lshrrev_b32_e32 v32, 16, v36
	v_lshrrev_b32_e32 v34, 16, v45
	v_and_or_b32 v32, v39, s4, v32
	v_and_or_b32 v33, v38, s4, v33
	v_lshrrev_b32_e32 v36, 12, v36
	v_lshrrev_b32_e32 v39, 8, v39
	v_lshrrev_b32_e32 v37, 4, v37
	v_and_b32_e32 v38, 0xf000, v38
	v_lshrrev_b32_e32 v35, 16, v47
	v_and_or_b32 v34, v157, s4, v34
	v_and_b32_e32 v39, 0xf0, v39
	v_and_b32_e32 v37, 0xf00, v37
	v_lshlrev_b32_e32 v45, 4, v45
	v_lshlrev_b32_e32 v157, 8, v157
	v_and_or_b32 v36, v36, 15, v38
	v_and_or_b32 v35, v156, s4, v35
	v_and_b32_e32 v45, 0xf0000, v45
	v_and_b32_e32 v157, 0xf00000, v157
	v_lshlrev_b32_e32 v47, 12, v47
	v_lshlrev_b32_e32 v156, 16, v156
	v_or3_b32 v36, v36, v39, v37
	v_and_b32_e32 v47, 0xf000000, v47
	v_and_b32_e32 v156, 0xf0000000, v156
	v_or3_b32 v36, v36, v45, v157
	v_or3_b32 v36, v36, v47, v156
	global_store_dwordx4 v[124:125], v[32:35], off nt
	global_store_dword v[126:127], v36, off nt
	v_add_u32_e32 v36, 0x800, v116
	v_add_u32_e32 v37, 0x800, v118
	v_add_u32_e32 v38, 0x800, v119
	v_add_u32_e32 v39, 0x800, v117
	v_add_u32_e32 v45, 0x800, v120
	v_lshrrev_b32_e32 v33, 16, v37
	v_lshrrev_b32_e32 v32, 16, v36
	v_add_u32_e32 v47, 0x800, v122
	v_add_u32_e32 v157, 0x800, v121
	v_lshrrev_b32_e32 v34, 16, v45
	v_and_or_b32 v32, v39, s4, v32
	v_and_or_b32 v33, v38, s4, v33
	v_lshrrev_b32_e32 v36, 12, v36
	v_lshrrev_b32_e32 v39, 8, v39
	v_lshrrev_b32_e32 v37, 4, v37
	v_and_b32_e32 v38, 0xf000, v38
	v_add_u32_e32 v156, 0x800, v123
	v_lshrrev_b32_e32 v35, 16, v47
	v_and_or_b32 v34, v157, s4, v34
	v_and_b32_e32 v39, 0xf0, v39
	v_and_b32_e32 v37, 0xf00, v37
	v_lshlrev_b32_e32 v45, 4, v45
	v_lshlrev_b32_e32 v157, 8, v157
	v_and_or_b32 v36, v36, 15, v38
	v_and_or_b32 v35, v156, s4, v35
	v_and_b32_e32 v45, 0xf0000, v45
	v_and_b32_e32 v157, 0xf00000, v157
	v_lshlrev_b32_e32 v47, 12, v47
	v_lshlrev_b32_e32 v156, 16, v156
	v_or3_b32 v36, v36, v39, v37
	v_and_b32_e32 v47, 0xf000000, v47
	v_and_b32_e32 v156, 0xf0000000, v156
	v_or3_b32 v36, v36, v45, v157
	v_or3_b32 v36, v36, v47, v156
	global_store_dwordx4 v[136:137], v[32:35], off nt
	global_store_dword v[138:139], v36, off nt
	v_add_u32_e32 v36, 0x800, v128
	v_add_u32_e32 v37, 0x800, v130
	v_add_u32_e32 v38, 0x800, v131
	v_add_u32_e32 v39, 0x800, v129
	v_add_u32_e32 v45, 0x800, v132
	v_lshrrev_b32_e32 v33, 16, v37
	v_lshrrev_b32_e32 v32, 16, v36
	v_add_u32_e32 v47, 0x800, v134
	v_add_u32_e32 v157, 0x800, v133
	v_lshrrev_b32_e32 v34, 16, v45
	v_and_or_b32 v32, v39, s4, v32
	v_and_or_b32 v33, v38, s4, v33
	v_lshrrev_b32_e32 v36, 12, v36
	v_lshrrev_b32_e32 v39, 8, v39
	v_lshrrev_b32_e32 v37, 4, v37
	v_and_b32_e32 v38, 0xf000, v38
	v_add_u32_e32 v156, 0x800, v135
	v_lshrrev_b32_e32 v35, 16, v47
	v_and_or_b32 v34, v157, s4, v34
	v_and_b32_e32 v39, 0xf0, v39
	v_and_b32_e32 v37, 0xf00, v37
	v_lshlrev_b32_e32 v45, 4, v45
	v_lshlrev_b32_e32 v157, 8, v157
	v_and_or_b32 v36, v36, 15, v38
	v_and_or_b32 v35, v156, s4, v35
	v_and_b32_e32 v45, 0xf0000, v45
	v_and_b32_e32 v157, 0xf00000, v157
	v_lshlrev_b32_e32 v47, 12, v47
	v_lshlrev_b32_e32 v156, 16, v156
	v_or3_b32 v36, v36, v39, v37
	v_and_b32_e32 v47, 0xf000000, v47
	v_and_b32_e32 v156, 0xf0000000, v156
	v_or3_b32 v36, v36, v45, v157
	v_or3_b32 v36, v36, v47, v156
	global_store_dwordx4 v[140:141], v[32:35], off nt
	global_store_dword v[142:143], v36, off nt
	v_add_u32_e32 v36, 0x800, v148
	v_add_u32_e32 v37, 0x800, v150
	v_add_u32_e32 v38, 0x800, v151
	v_add_u32_e32 v39, 0x800, v149
	v_add_u32_e32 v45, 0x800, v152
	v_lshrrev_b32_e32 v33, 16, v37
	v_lshrrev_b32_e32 v32, 16, v36
	v_add_u32_e32 v47, 0x800, v154
	v_add_u32_e32 v157, 0x800, v153
	v_lshrrev_b32_e32 v34, 16, v45
	v_and_or_b32 v32, v39, s4, v32
	v_and_or_b32 v33, v38, s4, v33
	v_lshrrev_b32_e32 v36, 12, v36
	v_lshrrev_b32_e32 v39, 8, v39
	v_lshrrev_b32_e32 v37, 4, v37
	v_and_b32_e32 v38, 0xf000, v38
	v_add_u32_e32 v156, 0x800, v155
	v_lshrrev_b32_e32 v35, 16, v47
	v_and_or_b32 v34, v157, s4, v34
	v_and_b32_e32 v39, 0xf0, v39
	v_and_b32_e32 v37, 0xf00, v37
	v_lshlrev_b32_e32 v45, 4, v45
	v_lshlrev_b32_e32 v157, 8, v157
	v_and_or_b32 v36, v36, 15, v38
	v_and_or_b32 v35, v156, s4, v35
	v_and_b32_e32 v45, 0xf0000, v45
	v_and_b32_e32 v157, 0xf00000, v157
	v_lshlrev_b32_e32 v47, 12, v47
	v_lshlrev_b32_e32 v156, 16, v156
	v_or3_b32 v36, v36, v39, v37
	v_and_b32_e32 v47, 0xf000000, v47
	v_and_b32_e32 v156, 0xf0000000, v156
	v_or3_b32 v36, v36, v45, v157
	v_or3_b32 v36, v36, v47, v156
	global_store_dwordx4 v[144:145], v[32:35], off nt
	global_store_dword v[146:147], v36, off nt

; #define GAS __attribute__((address_space(1)))
; __device__ __forceinline__ void h24_load(const unsigned char* Hb, size_t r, int lane, float (&v)[4][8]) {
; #pragma unroll
;     for (int j = 0; j < 4; ++j) { const size_t e = r * 2048 + 8 * (lane + 64 * j);
;         const v4u hi = __builtin_nontemporal_load((const GAS v4u*)(Hb + e * 2)); const unsigned lo = __builtin_nontemporal_load((const GAS unsigned*)(Hb + H_LO_OFF + (e >> 1)));
; #pragma unroll
;         for (int q = 0; q < 4; ++q) {
;             v[j][2 * q] = __builtin_bit_cast(float, ((hi[q] & 0xffffu) << 16) | (((lo >> (8 * q)) & 0xfu) << 12));
;             v[j][2 * q + 1] = __builtin_bit_cast(float, (hi[q] & 0xffff0000u) | (((lo >> (8 * q + 4)) & 0xfu) << 12)); } }
; }
; __device__ __forceinline__ void norm_phase(bool from_input, int gw, int NGW, int lane_in, float* H, const float* x_in, const float* c_in, const float* gain, const float* modL, int js, int jc, bf16* XN, ...
;     ...
;         if (from_input || (pend && s_from_input)) f32_load8_nt(s < 256 ? c_in + ((size_t)b * 256 + s) * 2048 : x_in + ((size_t)b * 8192 + (s - 256)) * 2048, lane, v);
;         else h24_load(Hb, (size_t)r, lane, v);
;         if (DLT && s >= 256) { bf16_add8(DLT + (size_t)r * 2048, lane, v); h24_store(Hb, (size_t)r, lane, v); }
.LBB0_1486:
	s_lshl_b64 s[34:35], s[20:21], 11
	v_mov_b32_e32 v37, s35
	v_or_b32_e32 v36, s34, v40
	v_lshl_add_u64 v[124:125], v[36:37], 1, s[90:91]
	v_lshrrev_b64 v[36:37], 1, v[36:37]
	v_lshl_add_u64 v[126:127], s[78:79], 0, v[36:37]
	global_load_dwordx4 v[208:211], v[124:125], off nt
	global_load_dword v242, v[126:127], off nt
	v_mov_b32_e32 v207, s35
	v_or_b32_e32 v206, s34, v42
	v_lshl_add_u64 v[136:137], v[206:207], 1, s[90:91]
	v_lshrrev_b64 v[206:207], 1, v[206:207]
	v_lshl_add_u64 v[138:139], s[78:79], 0, v[206:207]
	global_load_dwordx4 v[212:215], v[136:137], off nt
	global_load_dword v243, v[138:139], off nt
	v_mov_b32_e32 v207, s35
	v_or_b32_e32 v206, s34, v44
	v_lshl_add_u64 v[140:141], v[206:207], 1, s[90:91]
	v_lshrrev_b64 v[206:207], 1, v[206:207]
	v_lshl_add_u64 v[142:143], s[78:79], 0, v[206:207]
	global_load_dwordx4 v[216:219], v[140:141], off nt
	global_load_dword v244, v[142:143], off nt
	v_mov_b32_e32 v207, s35
	v_or_b32_e32 v206, s34, v46
	v_lshl_add_u64 v[144:145], v[206:207], 1, s[90:91]
	v_lshrrev_b64 v[206:207], 1, v[206:207]
	v_lshl_add_u64 v[146:147], s[78:79], 0, v[206:207]
	global_load_dwordx4 v[220:223], v[144:145], off nt
	global_load_dword v245, v[146:147], off nt
	v_lshl_add_u64 v[240:241], v[48:49], 0, s[34:35]
	v_lshl_add_u64 v[240:241], v[240:241], 0, s[34:35]
	global_load_dwordx4 v[224:227], v[240:241], off nt
	global_load_dwordx4 v[228:231], v[240:241], off offset:1024 nt
	global_load_dwordx4 v[232:235], v[240:241], off offset:2048 nt
	global_load_dwordx4 v[236:239], v[240:241], off offset:3072 nt
	s_cmpk_lt_u32 s10, 0x100
	s_waitcnt vmcnt(11)
	v_and_b32_e32 v37, 0xffff0000, v208
	s_waitcnt vmcnt(10)
	v_lshlrev_b32_e32 v39, 12, v242
	v_lshlrev_b32_e32 v32, 16, v208
	v_lshlrev_b32_e32 v38, 8, v242
	v_and_b32_e32 v39, 0xf000, v39
	v_and_b32_e32 v38, 0xf000, v38
	v_or_b32_e32 v108, v39, v32
	v_lshlrev_b32_e32 v32, 4, v242
	v_or_b32_e32 v109, v38, v37
	v_and_b32_e32 v37, 0xffff0000, v209
	v_lshlrev_b32_e32 v33, 16, v209
	v_and_b32_e32 v38, 0xf000, v242
	v_and_b32_e32 v32, 0xf000, v32
	v_or_b32_e32 v111, v38, v37
	v_or_b32_e32 v110, v32, v33
	v_and_b32_e32 v32, 0xffff0000, v210
	v_lshlrev_b32_e32 v33, 16, v210
	v_lshrrev_b32_e32 v34, 8, v242
	v_lshrrev_b32_e32 v37, 4, v242
	v_and_b32_e32 v34, 0xf000, v34
	v_and_b32_e32 v37, 0xf000, v37
	v_or_b32_e32 v113, v34, v32
	v_or_b32_e32 v112, v37, v33
	v_and_b32_e32 v32, 0xffff0000, v211
	v_lshlrev_b32_e32 v33, 16, v211
	v_lshrrev_b32_e32 v34, 12, v242
	v_and_b32_sdwa v35, v242, s5 dst_sel:DWORD dst_unused:UNUSED_PAD src0_sel:WORD_1 src1_sel:DWORD
	v_mov_b32_e32 v37, s35
	v_or_b32_e32 v36, s34, v42
	v_lshl_add_u64 v[136:137], v[36:37], 1, s[90:91]
	v_lshrrev_b64 v[36:37], 1, v[36:37]
	v_and_b32_e32 v34, 0xf000, v34
	v_lshl_add_u64 v[138:139], s[78:79], 0, v[36:37]
	v_or_b32_e32 v115, v35, v32
	v_or_b32_e32 v114, v34, v33
	s_waitcnt vmcnt(9)
	v_and_b32_e32 v37, 0xffff0000, v212
	s_waitcnt vmcnt(8)
	v_lshlrev_b32_e32 v39, 12, v243
	v_lshlrev_b32_e32 v32, 16, v212
	v_lshlrev_b32_e32 v38, 8, v243
	v_and_b32_e32 v39, 0xf000, v39
	v_and_b32_e32 v38, 0xf000, v38
	v_or_b32_e32 v116, v39, v32
	v_lshlrev_b32_e32 v32, 4, v243
	v_or_b32_e32 v117, v38, v37
	v_and_b32_e32 v37, 0xffff0000, v213
	v_lshlrev_b32_e32 v33, 16, v213
	v_and_b32_e32 v38, 0xf000, v243
	v_and_b32_e32 v32, 0xf000, v32
	v_or_b32_e32 v119, v38, v37
	v_or_b32_e32 v118, v32, v33
	v_and_b32_e32 v32, 0xffff0000, v214
	v_lshlrev_b32_e32 v33, 16, v214
	v_lshrrev_b32_e32 v34, 8, v243
	v_lshrrev_b32_e32 v37, 4, v243
	v_and_b32_e32 v34, 0xf000, v34
	v_and_b32_e32 v37, 0xf000, v37
	v_or_b32_e32 v121, v34, v32
	v_or_b32_e32 v120, v37, v33
	v_and_b32_e32 v32, 0xffff0000, v215
	v_lshlrev_b32_e32 v33, 16, v215
	v_lshrrev_b32_e32 v34, 12, v243
	v_and_b32_sdwa v35, v243, s5 dst_sel:DWORD dst_unused:UNUSED_PAD src0_sel:WORD_1 src1_sel:DWORD
	v_mov_b32_e32 v37, s35
	v_or_b32_e32 v36, s34, v44
	v_lshl_add_u64 v[140:141], v[36:37], 1, s[90:91]
	v_lshrrev_b64 v[36:37], 1, v[36:37]
	v_and_b32_e32 v34, 0xf000, v34
	v_lshl_add_u64 v[142:143], s[78:79], 0, v[36:37]
	v_or_b32_e32 v123, v35, v32
	v_or_b32_e32 v122, v34, v33
	s_waitcnt vmcnt(7)
	v_and_b32_e32 v37, 0xffff0000, v216
	s_waitcnt vmcnt(6)
	v_lshlrev_b32_e32 v39, 12, v244
	v_lshlrev_b32_e32 v32, 16, v216
	v_lshlrev_b32_e32 v38, 8, v244
	v_and_b32_e32 v39, 0xf000, v39
	v_and_b32_e32 v38, 0xf000, v38
	v_or_b32_e32 v128, v39, v32
	v_lshlrev_b32_e32 v32, 4, v244
	v_or_b32_e32 v129, v38, v37
	v_and_b32_e32 v37, 0xffff0000, v217
	v_lshlrev_b32_e32 v33, 16, v217
	v_and_b32_e32 v38, 0xf000, v244
	v_and_b32_e32 v32, 0xf000, v32
	v_or_b32_e32 v131, v38, v37
	v_or_b32_e32 v130, v32, v33
	v_and_b32_e32 v32, 0xffff0000, v218
	v_lshlrev_b32_e32 v33, 16, v218
	v_lshrrev_b32_e32 v34, 8, v244
	v_lshrrev_b32_e32 v37, 4, v244
	v_and_b32_e32 v34, 0xf000, v34
	v_and_b32_e32 v37, 0xf000, v37
	v_or_b32_e32 v133, v34, v32
	v_or_b32_e32 v132, v37, v33
	v_and_b32_e32 v32, 0xffff0000, v219
	v_lshlrev_b32_e32 v33, 16, v219
	v_lshrrev_b32_e32 v34, 12, v244
	v_and_b32_sdwa v35, v244, s5 dst_sel:DWORD dst_unused:UNUSED_PAD src0_sel:WORD_1 src1_sel:DWORD
	v_mov_b32_e32 v37, s35
	v_or_b32_e32 v36, s34, v46
	v_lshl_add_u64 v[144:145], v[36:37], 1, s[90:91]
	v_lshrrev_b64 v[36:37], 1, v[36:37]
	v_and_b32_e32 v34, 0xf000, v34
	v_lshl_add_u64 v[146:147], s[78:79], 0, v[36:37]
	v_or_b32_e32 v135, v35, v32
	v_or_b32_e32 v134, v34, v33
	s_waitcnt vmcnt(5)
	v_and_b32_e32 v37, 0xffff0000, v220
	s_waitcnt vmcnt(4)
	v_lshlrev_b32_e32 v39, 12, v245
	v_lshlrev_b32_e32 v32, 16, v220
	v_lshlrev_b32_e32 v38, 8, v245
	v_and_b32_e32 v39, 0xf000, v39
	v_and_b32_e32 v38, 0xf000, v38
	v_or_b32_e32 v148, v39, v32
	v_lshlrev_b32_e32 v32, 4, v245
	v_or_b32_e32 v149, v38, v37
	v_and_b32_e32 v37, 0xffff0000, v221
	v_lshlrev_b32_e32 v33, 16, v221
	v_and_b32_e32 v32, 0xf000, v32
	v_and_b32_e32 v38, 0xf000, v245
	v_or_b32_e32 v150, v32, v33
	v_and_b32_e32 v32, 0xffff0000, v222
	v_lshlrev_b32_e32 v33, 16, v222
	v_lshrrev_b32_e32 v34, 8, v245
	v_or_b32_e32 v151, v38, v37
	v_lshrrev_b32_e32 v37, 4, v245
	v_and_b32_e32 v34, 0xf000, v34
	v_and_b32_e32 v37, 0xf000, v37
	v_or_b32_e32 v153, v34, v32
	v_lshrrev_b32_e32 v34, 12, v245
	v_or_b32_e32 v152, v37, v33
	v_and_b32_e32 v32, 0xffff0000, v223
	v_lshlrev_b32_e32 v33, 16, v223
	v_and_b32_sdwa v35, v245, s5 dst_sel:DWORD dst_unused:UNUSED_PAD src0_sel:WORD_1 src1_sel:DWORD
	v_and_b32_e32 v34, 0xf000, v34
	v_or_b32_e32 v155, v35, v32
	v_or_b32_e32 v154, v34, v33
	s_cbranch_scc1 .LBB0_1488
; #define GAS __attribute__((address_space(1)))
; __device__ __forceinline__ void h24_store(unsigned char* Hb, size_t r, int lane, const float (&v)[4][8]) {
; #pragma unroll
;     for (int j = 0; j < 4; ++j) { const size_t e = r * 2048 + 8 * (lane + 64 * j); unsigned u[8];
; #pragma unroll
;         for (int q = 0; q < 8; ++q) u[q] = __builtin_bit_cast(unsigned, v[j][q]) + 0x800u;
;         v4u hi; unsigned lo = 0u;
; #pragma unroll
;         for (int q = 0; q < 4; ++q) hi[q] = (u[2 * q] >> 16) | (u[2 * q + 1] & 0xffff0000u);
; #pragma unroll
;         for (int q = 0; q < 8; ++q) lo |= ((u[q] >> 12) & 0xfu) << (4 * q);
;         __builtin_nontemporal_store(hi, (GAS v4u*)(Hb + e * 2)); __builtin_nontemporal_store(lo, (GAS unsigned*)(Hb + H_LO_OFF + (e >> 1))); }
; }
; __device__ __forceinline__ void f32_load8(const float* row, int lane, float (&v)[4][8]) {
; #pragma unroll
;     for (int j = 0; j < 4; ++j) { const GAS f32x4* p = (const GAS f32x4*)(row + 8 * (lane + 64 * j)); const f32x4 a = p[0], b = p[1];
; #pragma unroll
;         for (int q = 0; q < 4; ++q) { v[j][q] = a[q]; v[j][4 + q] = b[q]; } }
; }
; __device__ __forceinline__ void f32_load8_nt(const float* row, int lane, float (&v)[4][8]) {
; #pragma unroll
;     for (int j = 0; j < 4; ++j) { const GAS f32x4* p = (const GAS f32x4*)(row + 8 * (lane + 64 * j)); const f32x4 a = __builtin_nontemporal_load(p), b = __builtin_nontemporal_load(p + 1);
; #pragma unroll
;         for (int q = 0; q < 4; ++q) { v[j][q] = a[q]; v[j][4 + q] = b[q]; } }
; }
; __device__ __forceinline__ void bf16_add8(const bf16* row, int lane, float (&v)[4][8]) {
; #pragma unroll
;     for (int j = 0; j < 4; ++j) { const v4u d = __builtin_nontemporal_load((const GAS v4u*)(row + 8 * (lane + 64 * j)));
; #pragma unroll
;         for (int q = 0; q < 4; ++q) { v[j][2 * q] += bf2f(d[q] & 0xffffu); v[j][2 * q + 1] += bf2f(d[q] >> 16); } }
; }
	s_lshl_b64 s[34:35], s[20:21], 12
	v_lshl_add_u64 v[36:37], v[48:49], 0, s[34:35]
	s_waitcnt vmcnt(3)
	v_and_b32_e32 v39, 0xffff0000, v224
	v_lshlrev_b32_e32 v38, 16, v224
	v_pk_add_f32 v[108:109], v[108:109], v[38:39]
	v_and_b32_e32 v39, 0xffff0000, v225
	v_lshlrev_b32_e32 v38, 16, v225
	v_and_b32_e32 v33, 0xffff0000, v226
	v_lshlrev_b32_e32 v32, 16, v226
	v_pk_add_f32 v[112:113], v[112:113], v[32:33]
	v_and_b32_e32 v33, 0xffff0000, v227
	v_lshlrev_b32_e32 v32, 16, v227
	v_pk_add_f32 v[114:115], v[114:115], v[32:33]
	v_pk_add_f32 v[110:111], v[110:111], v[38:39]
	v_add_u32_e32 v45, 0x800, v112
	v_add_u32_e32 v47, 0x800, v114
	v_add_u32_e32 v157, 0x800, v113
	v_add_u32_e32 v156, 0x800, v115
	s_waitcnt vmcnt(2)
	v_and_b32_e32 v39, 0xffff0000, v228
	v_lshlrev_b32_e32 v38, 16, v228
	v_pk_add_f32 v[116:117], v[116:117], v[38:39]
	v_and_b32_e32 v39, 0xffff0000, v229
	v_lshlrev_b32_e32 v38, 16, v229
	v_and_b32_e32 v33, 0xffff0000, v230
	v_lshlrev_b32_e32 v32, 16, v230
	v_pk_add_f32 v[120:121], v[120:121], v[32:33]
	v_and_b32_e32 v33, 0xffff0000, v231
	v_lshlrev_b32_e32 v32, 16, v231
	v_pk_add_f32 v[122:123], v[122:123], v[32:33]
	v_pk_add_f32 v[118:119], v[118:119], v[38:39]
	s_waitcnt vmcnt(1)
	v_and_b32_e32 v39, 0xffff0000, v232
	v_lshlrev_b32_e32 v38, 16, v232
	v_pk_add_f32 v[128:129], v[128:129], v[38:39]
	v_and_b32_e32 v39, 0xffff0000, v233
	v_lshlrev_b32_e32 v38, 16, v233
	v_and_b32_e32 v33, 0xffff0000, v234
	v_lshlrev_b32_e32 v32, 16, v234
	v_pk_add_f32 v[132:133], v[132:133], v[32:33]
	v_and_b32_e32 v33, 0xffff0000, v235
	v_lshlrev_b32_e32 v32, 16, v235
	v_pk_add_f32 v[134:135], v[134:135], v[32:33]
	v_pk_add_f32 v[130:131], v[130:131], v[38:39]
	v_add_u32_e32 v38, 0x800, v111
	v_add_u32_e32 v39, 0x800, v109
	s_waitcnt vmcnt(0)
	v_and_b32_e32 v37, 0xffff0000, v236
	v_lshlrev_b32_e32 v36, 16, v236
	v_pk_add_f32 v[148:149], v[148:149], v[36:37]
	v_and_b32_e32 v37, 0xffff0000, v237
	v_lshlrev_b32_e32 v36, 16, v237
	v_and_b32_e32 v33, 0xffff0000, v238
	v_lshlrev_b32_e32 v32, 16, v238
	v_pk_add_f32 v[150:151], v[150:151], v[36:37]
	v_pk_add_f32 v[152:153], v[152:153], v[32:33]
	v_and_b32_e32 v33, 0xffff0000, v239
	v_lshlrev_b32_e32 v32, 16, v239
	v_add_u32_e32 v36, 0x800, v108
	v_add_u32_e32 v37, 0x800, v110
	v_pk_add_f32 v[154:155], v[154:155], v[32:33]
	v_lshrrev_b32_e32 v33, 16, v37
	v_lshrrev_b32_e32 v32, 16, v36
	v_lshrrev_b32_e32 v34, 16, v45
	v_and_or_b32 v32, v39, s4, v32
	v_and_or_b32 v33, v38, s4, v33
	v_lshrrev_b32_e32 v36, 12, v36
	v_lshrrev_b32_e32 v39, 8, v39
	v_lshrrev_b32_e32 v37, 4, v37
	v_and_b32_e32 v38, 0xf000, v38
	v_lshrrev_b32_e32 v35, 16, v47
	v_and_or_b32 v34, v157, s4, v34
	v_and_b32_e32 v39, 0xf0, v39
	v_and_b32_e32 v37, 0xf00, v37
	v_lshlrev_b32_e32 v45, 4, v45
	v_lshlrev_b32_e32 v157, 8, v157
	v_and_or_b32 v36, v36, 15, v38
	v_and_or_b32 v35, v156, s4, v35
	v_and_b32_e32 v45, 0xf0000, v45
	v_and_b32_e32 v157, 0xf00000, v157
	v_lshlrev_b32_e32 v47, 12, v47
	v_lshlrev_b32_e32 v156, 16, v156
	v_or3_b32 v36, v36, v39, v37
	v_and_b32_e32 v47, 0xf000000, v47
	v_and_b32_e32 v156, 0xf0000000, v156
	v_or3_b32 v36, v36, v45, v157
	v_or3_b32 v36, v36, v47, v156
	global_store_dwordx4 v[124:125], v[32:35], off nt
	global_store_dword v[126:127], v36, off nt
	v_add_u32_e32 v36, 0x800, v116
	v_add_u32_e32 v37, 0x800, v118
	v_add_u32_e32 v38, 0x800, v119
	v_add_u32_e32 v39, 0x800, v117
	v_add_u32_e32 v45, 0x800, v120
	v_lshrrev_b32_e32 v33, 16, v37
	v_lshrrev_b32_e32 v32, 16, v36
	v_add_u32_e32 v47, 0x800, v122
	v_add_u32_e32 v157, 0x800, v121
	v_lshrrev_b32_e32 v34, 16, v45
	v_and_or_b32 v32, v39, s4, v32
	v_and_or_b32 v33, v38, s4, v33
	v_lshrrev_b32_e32 v36, 12, v36
	v_lshrrev_b32_e32 v39, 8, v39
	v_lshrrev_b32_e32 v37, 4, v37
	v_and_b32_e32 v38, 0xf000, v38
	v_add_u32_e32 v156, 0x800, v123
	v_lshrrev_b32_e32 v35, 16, v47
	v_and_or_b32 v34, v157, s4, v34
	v_and_b32_e32 v39, 0xf0, v39
	v_and_b32_e32 v37, 0xf00, v37
	v_lshlrev_b32_e32 v45, 4, v45
	v_lshlrev_b32_e32 v157, 8, v157
	v_and_or_b32 v36, v36, 15, v38
	v_and_or_b32 v35, v156, s4, v35
	v_and_b32_e32 v45, 0xf0000, v45
	v_and_b32_e32 v157, 0xf00000, v157
	v_lshlrev_b32_e32 v47, 12, v47
	v_lshlrev_b32_e32 v156, 16, v156
	v_or3_b32 v36, v36, v39, v37
	v_and_b32_e32 v47, 0xf000000, v47
	v_and_b32_e32 v156, 0xf0000000, v156
	v_or3_b32 v36, v36, v45, v157
	v_or3_b32 v36, v36, v47, v156
	global_store_dwordx4 v[136:137], v[32:35], off nt
	global_store_dword v[138:139], v36, off nt
	v_add_u32_e32 v36, 0x800, v128
	v_add_u32_e32 v37, 0x800, v130
	v_add_u32_e32 v38, 0x800, v131
	v_add_u32_e32 v39, 0x800, v129
	v_add_u32_e32 v45, 0x800, v132
	v_lshrrev_b32_e32 v33, 16, v37
	v_lshrrev_b32_e32 v32, 16, v36
	v_add_u32_e32 v47, 0x800, v134
	v_add_u32_e32 v157, 0x800, v133
	v_lshrrev_b32_e32 v34, 16, v45
	v_and_or_b32 v32, v39, s4, v32
	v_and_or_b32 v33, v38, s4, v33
	v_lshrrev_b32_e32 v36, 12, v36
	v_lshrrev_b32_e32 v39, 8, v39
	v_lshrrev_b32_e32 v37, 4, v37
	v_and_b32_e32 v38, 0xf000, v38
	v_add_u32_e32 v156, 0x800, v135
	v_lshrrev_b32_e32 v35, 16, v47
	v_and_or_b32 v34, v157, s4, v34
	v_and_b32_e32 v39, 0xf0, v39
	v_and_b32_e32 v37, 0xf00, v37
	v_lshlrev_b32_e32 v45, 4, v45
	v_lshlrev_b32_e32 v157, 8, v157
	v_and_or_b32 v36, v36, 15, v38
	v_and_or_b32 v35, v156, s4, v35
	v_and_b32_e32 v45, 0xf0000, v45
	v_and_b32_e32 v157, 0xf00000, v157
	v_lshlrev_b32_e32 v47, 12, v47
	v_lshlrev_b32_e32 v156, 16, v156
	v_or3_b32 v36, v36, v39, v37
	v_and_b32_e32 v47, 0xf000000, v47
	v_and_b32_e32 v156, 0xf0000000, v156
	v_or3_b32 v36, v36, v45, v157
	v_or3_b32 v36, v36, v47, v156
	global_store_dwordx4 v[140:141], v[32:35], off nt
	global_store_dword v[142:143], v36, off nt
	v_add_u32_e32 v36, 0x800, v148
	v_add_u32_e32 v37, 0x800, v150
	v_add_u32_e32 v38, 0x800, v151
	v_add_u32_e32 v39, 0x800, v149
	v_add_u32_e32 v45, 0x800, v152
	v_lshrrev_b32_e32 v33, 16, v37
	v_lshrrev_b32_e32 v32, 16, v36
	v_add_u32_e32 v47, 0x800, v154
	v_add_u32_e32 v157, 0x800, v153
	v_lshrrev_b32_e32 v34, 16, v45
	v_and_or_b32 v32, v39, s4, v32
	v_and_or_b32 v33, v38, s4, v33
	v_lshrrev_b32_e32 v36, 12, v36
	v_lshrrev_b32_e32 v39, 8, v39
	v_lshrrev_b32_e32 v37, 4, v37
	v_and_b32_e32 v38, 0xf000, v38
	v_add_u32_e32 v156, 0x800, v155
	v_lshrrev_b32_e32 v35, 16, v47
	v_and_or_b32 v34, v157, s4, v34
	v_and_b32_e32 v39, 0xf0, v39
	v_and_b32_e32 v37, 0xf00, v37
	v_lshlrev_b32_e32 v45, 4, v45
	v_lshlrev_b32_e32 v157, 8, v157
	v_and_or_b32 v36, v36, 15, v38
	v_and_or_b32 v35, v156, s4, v35
	v_and_b32_e32 v45, 0xf0000, v45
	v_and_b32_e32 v157, 0xf00000, v157
	v_lshlrev_b32_e32 v47, 12, v47
	v_lshlrev_b32_e32 v156, 16, v156
	v_or3_b32 v36, v36, v39, v37
	v_and_b32_e32 v47, 0xf000000, v47
	v_and_b32_e32 v156, 0xf0000000, v156
	v_or3_b32 v36, v36, v45, v157
	v_or3_b32 v36, v36, v47, v156
	global_store_dwordx4 v[144:145], v[32:35], off nt
	global_store_dword v[146:147], v36, off nt
